# prompt-MLA tile loop: asymmetric wave priority (waves 0-3 prio 2) for ping-pong of the two waves per SIMD
# baseline (speedup 1.0000x reference)
.LBB0_1055:
	s_sub_i32 s1, s12, 32
	s_lshr_b32 s1, s1, 1
	s_sub_i32 s9, 31, s1
	v_lshlrev_b32_e32 v1, 3, v165
	s_lshl_b32 s13, s9, 8
	s_lshl_b32 s17, s9, 2
	v_and_b32_e32 v5, 24, v1
	v_and_b32_e32 v2, 0xc0, v2
	v_readlane_b32 s9, v253, 19
	v_and_b32_e32 v173, 31, v164
	v_and_b32_e32 v4, 32, v4
	v_add3_u32 v2, s9, v5, v2
	s_add_i32 s46, s13, s81
	v_and_b32_e32 v1, 0x100, v1
	v_add3_u32 v174, v2, v4, v1
	v_or_b32_e32 v4, s46, v173
	v_ashrrev_i32_e32 v5, 31, v4
	v_readlane_b32 s18, v254, 7
	v_readlane_b32 s13, v254, 34
	v_lshlrev_b64 v[4:5], 4, v[4:5]
	v_readlane_b32 s19, v254, 8
	s_add_i32 s9, s17, 4
	s_add_i32 s13, s17, s13
	v_or_b32_e32 v1, s16, v4
	v_mov_b64_e32 v[6:7], s[18:19]
	s_movk_i32 s17, 0x180
	v_lshrrev_b32_e32 v172, 5, v165
	v_mad_u64_u32 v[6:7], s[18:19], v1, s17, v[6:7]
	v_mad_i32_i24 v7, v5, s17, v7
	v_lshlrev_b32_e32 v2, 4, v172
	v_lshl_add_u64 v[4:5], v[6:7], 0, v[2:3]
	global_load_dwordx4 v[114:117], v[4:5], off
	global_load_dwordx4 v[118:121], v[4:5], off offset:32
	global_load_dwordx4 v[122:125], v[4:5], off offset:64
	global_load_dwordx4 v[126:129], v[4:5], off offset:96
	global_load_dwordx4 v[130:133], v[4:5], off offset:128
	global_load_dwordx4 v[134:137], v[4:5], off offset:160
	global_load_dwordx4 v[138:141], v[4:5], off offset:192
	global_load_dwordx4 v[142:145], v[4:5], off offset:224
	global_load_dwordx4 v[146:149], v[4:5], off offset:256
	global_load_dwordx4 v[150:153], v[4:5], off offset:288
	global_load_dwordx4 v[154:157], v[4:5], off offset:320
	global_load_dwordx4 v[158:161], v[4:5], off offset:352
	v_lshlrev_b32_e32 v1, 4, v164
	s_movk_i32 s17, 0x70
	v_and_b32_e32 v4, 0x70, v1
	v_bitop3_b32 v175, v2, v1, s17 bitop3:0x78
	s_movk_i32 s17, 0x60
	v_bitop3_b32 v178, v2, v4, s17 bitop3:0x36
	s_movk_i32 s17, 0xa0
	v_bitop3_b32 v180, v2, v4, s17 bitop3:0x36
	s_movk_i32 s17, 0xc0
	v_bitop3_b32 v181, v2, v4, s17 bitop3:0x36
	s_movk_i32 s17, 0xe0
	v_bitop3_b32 v182, v2, v4, s17 bitop3:0x36
	s_add_u32 s17, s52, 0x8000
	s_addc_u32 s18, s53, 0
	s_add_u32 s25, s48, 0x8000
	s_addc_u32 s28, s49, 0
	v_mov_b32_e32 v16, v3
	v_mov_b32_e32 v17, v3
	v_bitop3_b32 v176, v2, v4, 32 bitop3:0x36
	v_bitop3_b32 v177, v2, v4, 64 bitop3:0x36
	v_bitop3_b32 v179, v2, v4, s87 bitop3:0x36
	v_or_b32_e32 v183, 0x60e0, v2
	v_add_u32_e32 v184, 0, v2
	v_or_b32_e32 v185, 0x6000, v2
	s_add_u32 s48, s50, 0x200
	v_mov_b32_e32 v2, v3
	v_mov_b32_e32 v4, v3
	v_mov_b32_e32 v5, v3
	v_mov_b32_e32 v6, v3
	v_mov_b32_e32 v7, v3
	v_mov_b32_e32 v8, v3
	v_mov_b32_e32 v9, v3
	v_mov_b32_e32 v10, v3
	v_mov_b32_e32 v11, v3
	v_mov_b32_e32 v12, v3
	v_mov_b32_e32 v13, v3
	v_mov_b32_e32 v14, v3
	v_mov_b32_e32 v15, v3
	v_readlane_b32 s52, v255, 22
	v_mov_b64_e32 v[32:33], v[16:17]
	v_mov_b64_e32 v[48:49], v[16:17]
	v_mov_b64_e32 v[64:65], v[16:17]
	v_mov_b64_e32 v[80:81], v[16:17]
	s_mov_b32 s1, 2
	v_lshl_add_u32 v186, v173, 8, 0
	v_lshl_add_u32 v187, v173, 7, 0
	s_addc_u32 s49, s51, 0
	s_mov_b32 s36, 0
	v_mov_b32_e32 v162, 0
	s_mov_b64 s[50:51], 0
	v_readlane_b32 s53, v255, 23
	v_mov_b64_e32 v[30:31], v[14:15]
	v_mov_b64_e32 v[28:29], v[12:13]
	v_mov_b64_e32 v[26:27], v[10:11]
	v_mov_b64_e32 v[24:25], v[8:9]
	v_mov_b64_e32 v[22:23], v[6:7]
	v_mov_b64_e32 v[20:21], v[4:5]
	v_mov_b64_e32 v[18:19], v[2:3]
	v_mov_b64_e32 v[46:47], v[14:15]
	v_mov_b64_e32 v[44:45], v[12:13]
	v_mov_b64_e32 v[42:43], v[10:11]
	v_mov_b64_e32 v[40:41], v[8:9]
	v_mov_b64_e32 v[38:39], v[6:7]
	v_mov_b64_e32 v[36:37], v[4:5]
	v_mov_b64_e32 v[34:35], v[2:3]
	v_mov_b64_e32 v[62:63], v[14:15]
	v_mov_b64_e32 v[60:61], v[12:13]
	v_mov_b64_e32 v[58:59], v[10:11]
	v_mov_b64_e32 v[56:57], v[8:9]
	v_mov_b64_e32 v[54:55], v[6:7]
	v_mov_b64_e32 v[52:53], v[4:5]
	v_mov_b64_e32 v[50:51], v[2:3]
	s_mov_b32 s20, 0
	v_mov_b64_e32 v[78:79], v[14:15]
	v_mov_b64_e32 v[76:77], v[12:13]
	v_mov_b64_e32 v[74:75], v[10:11]
	v_mov_b64_e32 v[72:73], v[8:9]
	v_mov_b64_e32 v[70:71], v[6:7]
	v_mov_b64_e32 v[68:69], v[4:5]
	v_mov_b64_e32 v[66:67], v[2:3]
	v_readfirstlane_b32 s19, v0
	s_bitcmp1_b32 s19, 8
	s_cbranch_scc1 .Lpp_skip
	s_setprio 2
.Lpp_skip:
	s_waitcnt vmcnt(7)
	s_waitcnt vmcnt(6)
	s_waitcnt vmcnt(5)
	s_waitcnt vmcnt(4)
	s_waitcnt vmcnt(3)
	s_waitcnt vmcnt(2)
	s_waitcnt vmcnt(1)
	s_waitcnt vmcnt(0)
	s_add_i32 s37, s20, 1
	s_cmp_ge_u32 s37, s9
	s_mov_b64 s[54:55], -1
	s_cbranch_scc0 .LBB0_1057

.LBB0_1069:
	s_setprio 0
	v_mov_b32_e32 v2, v162
	s_nop 1
	v_permlane32_swap_b32_e32 v162, v2
	v_cmp_gt_u32_e32 vcc, 32, v165
	s_and_saveexec_b64 s[44:45], vcc
	s_cbranch_execz .LBB0_1071
	v_readlane_b32 s1, v254, 28
	v_add_f32_e32 v2, v162, v2
	s_nop 0
	v_lshl_add_u32 v1, v173, 2, s1
	ds_write_b32 v1, v2
.LBB0_1071:
	s_or_b64 exec, exec, s[44:45]
	s_ashr_i32 s47, s46, 31
	s_lshl_b64 s[18:19], s[46:47], 12
	v_readlane_b32 s1, v254, 29
	s_add_u32 s1, s1, s18
	v_readlane_b32 s9, v254, 30
	s_addc_u32 s9, s9, s19
	s_lshl_b32 s13, s16, 8
	s_add_u32 s46, s1, s13
	s_addc_u32 s47, s9, 0
	v_readlane_b32 s1, v254, 31
	s_add_u32 s1, s1, s18
	v_readlane_b32 s9, v254, 32
	s_addc_u32 s9, s9, s19
	s_add_u32 s44, s1, s13
	v_readlane_b32 s1, v254, 28
	s_waitcnt lgkmcnt(0)
	v_and_b32_e32 v1, 1, v164
	v_cmp_eq_u32_e32 vcc, 0, v1
	v_lshl_add_u32 v8, v172, 4, s1
	ds_read_b128 v[4:7], v8
	v_and_b32_e32 v2, 30, v164
	v_lshlrev_b32_e32 v9, 13, v172
	v_lshlrev_b32_e32 v1, 11, v1
	v_or3_b32 v1, v9, v1, v2
	s_waitcnt lgkmcnt(0)
	v_rcp_f32_e32 v4, v4
	v_rcp_f32_e32 v5, v5
	s_addc_u32 s45, s9, 0
	v_mul_f32_e32 v2, v66, v4
	v_mul_f32_e32 v9, v67, v5
	v_cndmask_b32_e32 v10, v2, v9, vcc
	ds_bpermute_b32 v10, v212, v10
	s_waitcnt lgkmcnt(0)
	v_cndmask_b32_e32 v11, v10, v2, vcc
	v_lshlrev_b32_e32 v2, 1, v1
	v_or_b32_e32 v13, 0x2000, v2
	v_or_b32_e32 v14, 0x8000, v2
	v_or_b32_e32 v15, 0xa000, v2
	v_or_b32_e32 v16, 0x10000, v2
	v_or_b32_e32 v17, 0x12000, v2
	v_or_b32_e32 v66, 0x18000, v2
	v_or_b32_e32 v82, 0x1a000, v2
	global_load_dword v83, v2, s[46:47]
	global_load_dword v84, v2, s[46:47] offset:64
	global_load_dword v85, v2, s[46:47] offset:128
	global_load_dword v86, v2, s[46:47] offset:192
	global_load_dword v87, v13, s[46:47]
	global_load_dword v88, v13, s[46:47] offset:64
	global_load_dword v89, v13, s[46:47] offset:128
	global_load_dword v90, v13, s[46:47] offset:192
	global_load_dword v91, v14, s[46:47]
	global_load_dword v92, v14, s[46:47] offset:64
	global_load_dword v93, v14, s[46:47] offset:128
	global_load_dword v94, v14, s[46:47] offset:192
	global_load_dword v95, v15, s[46:47]
	global_load_dword v96, v15, s[46:47] offset:64
	global_load_dword v97, v15, s[46:47] offset:128
	global_load_dword v98, v15, s[46:47] offset:192
	global_load_dword v99, v16, s[46:47]
	global_load_dword v100, v16, s[46:47] offset:64
	global_load_dword v101, v16, s[46:47] offset:128
	global_load_dword v102, v16, s[46:47] offset:192
	global_load_dword v103, v17, s[46:47]
	global_load_dword v104, v17, s[46:47] offset:64
	global_load_dword v105, v17, s[46:47] offset:128
	global_load_dword v106, v17, s[46:47] offset:192
	global_load_dword v107, v66, s[46:47]
	global_load_dword v108, v66, s[46:47] offset:64
	global_load_dword v109, v66, s[46:47] offset:128
	global_load_dword v110, v66, s[46:47] offset:192
	global_load_dword v111, v82, s[46:47]
	global_load_dword v112, v82, s[46:47] offset:64
	global_load_dword v113, v82, s[46:47] offset:128
	global_load_dword v114, v82, s[46:47] offset:192
	s_nop 0
	v_cndmask_b32_e32 v9, v9, v10, vcc
	s_waitcnt vmcnt(31)
	v_lshlrev_b32_e32 v10, 16, v83
	v_and_b32_e32 v1, 0xffff0000, v83
	v_mul_f32_e32 v10, v11, v10
	v_mul_f32_e32 v1, v9, v1
	v_cvt_pk_bf16_f32 v1, v10, v1
	global_store_dword v2, v1, s[44:45]
	v_mul_f32_e32 v1, v50, v4
	v_mul_f32_e32 v9, v51, v5
	v_cndmask_b32_e32 v10, v1, v9, vcc
	ds_bpermute_b32 v10, v212, v10
	s_waitcnt lgkmcnt(0)
	v_cndmask_b32_e32 v1, v10, v1, vcc
	v_cndmask_b32_e32 v9, v9, v10, vcc
	s_waitcnt vmcnt(31)
	v_lshlrev_b32_e32 v11, 16, v84
	v_and_b32_e32 v10, 0xffff0000, v84
	v_mul_f32_e32 v1, v1, v11
	v_mul_f32_e32 v9, v9, v10
	v_cvt_pk_bf16_f32 v1, v1, v9
	global_store_dword v2, v1, s[44:45] offset:64
	v_mul_f32_e32 v1, v34, v4
	v_mul_f32_e32 v9, v35, v5
	v_cndmask_b32_e32 v10, v1, v9, vcc
	ds_bpermute_b32 v10, v212, v10
	s_waitcnt lgkmcnt(0)
	v_cndmask_b32_e32 v1, v10, v1, vcc
	v_cndmask_b32_e32 v9, v9, v10, vcc
	s_waitcnt vmcnt(31)
	v_lshlrev_b32_e32 v11, 16, v85
	v_and_b32_e32 v10, 0xffff0000, v85
	v_mul_f32_e32 v1, v1, v11
	v_mul_f32_e32 v9, v9, v10
	v_cvt_pk_bf16_f32 v1, v1, v9
	global_store_dword v2, v1, s[44:45] offset:128
	v_mul_f32_e32 v1, v18, v4
	v_mul_f32_e32 v4, v19, v5
	v_cndmask_b32_e32 v5, v1, v4, vcc
	ds_bpermute_b32 v5, v212, v5
	s_waitcnt lgkmcnt(0)
	v_cndmask_b32_e32 v1, v5, v1, vcc
	v_cndmask_b32_e32 v4, v4, v5, vcc
	s_waitcnt vmcnt(31)
	v_lshlrev_b32_e32 v9, 16, v86
	v_and_b32_e32 v5, 0xffff0000, v86
	v_mul_f32_e32 v1, v1, v9
	v_mul_f32_e32 v4, v4, v5
	v_cvt_pk_bf16_f32 v1, v1, v4
	global_store_dword v2, v1, s[44:45] offset:192
	v_rcp_f32_e32 v1, v6
	v_rcp_f32_e32 v4, v7
	v_mul_f32_e32 v5, v68, v1
	v_mul_f32_e32 v6, v69, v4
	v_cndmask_b32_e32 v7, v5, v6, vcc
	ds_bpermute_b32 v7, v212, v7
	s_waitcnt lgkmcnt(0)
	v_cndmask_b32_e32 v5, v7, v5, vcc
	v_cndmask_b32_e32 v6, v6, v7, vcc
	v_or_b32_e32 v7, 0x2000, v2
	s_waitcnt vmcnt(31)
	v_lshlrev_b32_e32 v10, 16, v87
	v_and_b32_e32 v9, 0xffff0000, v87
	v_mul_f32_e32 v5, v5, v10
	v_mul_f32_e32 v6, v6, v9
	v_cvt_pk_bf16_f32 v5, v5, v6
	global_store_dword v7, v5, s[44:45]
	v_mul_f32_e32 v5, v52, v1
	v_mul_f32_e32 v6, v53, v4
	v_cndmask_b32_e32 v9, v5, v6, vcc
	ds_bpermute_b32 v9, v212, v9
	s_waitcnt lgkmcnt(0)
	v_cndmask_b32_e32 v5, v9, v5, vcc
	v_cndmask_b32_e32 v6, v6, v9, vcc
	s_waitcnt vmcnt(31)
	v_lshlrev_b32_e32 v10, 16, v88
	v_and_b32_e32 v9, 0xffff0000, v88
	v_mul_f32_e32 v5, v5, v10
	v_mul_f32_e32 v6, v6, v9
	v_cvt_pk_bf16_f32 v5, v5, v6
	global_store_dword v7, v5, s[44:45] offset:64
	v_mul_f32_e32 v5, v36, v1
	v_mul_f32_e32 v6, v37, v4
	v_cndmask_b32_e32 v9, v5, v6, vcc
	ds_bpermute_b32 v9, v212, v9
	v_mul_f32_e32 v1, v20, v1
	v_mul_f32_e32 v4, v21, v4
	s_waitcnt lgkmcnt(0)
	v_cndmask_b32_e32 v5, v9, v5, vcc
	v_cndmask_b32_e32 v6, v6, v9, vcc
	s_waitcnt vmcnt(31)
	v_lshlrev_b32_e32 v10, 16, v89
	v_and_b32_e32 v9, 0xffff0000, v89
	v_mul_f32_e32 v5, v5, v10
	v_mul_f32_e32 v6, v6, v9
	v_cvt_pk_bf16_f32 v5, v5, v6
	global_store_dword v7, v5, s[44:45] offset:128
	v_cndmask_b32_e32 v5, v1, v4, vcc
	ds_bpermute_b32 v5, v212, v5
	s_waitcnt lgkmcnt(0)
	v_cndmask_b32_e32 v1, v5, v1, vcc
	v_cndmask_b32_e32 v4, v4, v5, vcc
	s_waitcnt vmcnt(31)
	v_lshlrev_b32_e32 v6, 16, v90
	v_and_b32_e32 v5, 0xffff0000, v90
	v_mul_f32_e32 v1, v1, v6
	v_mul_f32_e32 v4, v4, v5
	v_cvt_pk_bf16_f32 v1, v1, v4
	global_store_dword v7, v1, s[44:45] offset:192
	ds_read_b128 v[4:7], v8 offset:32
	s_waitcnt lgkmcnt(0)
	v_rcp_f32_e32 v4, v4
	v_rcp_f32_e32 v5, v5
	v_mul_f32_e32 v1, v70, v4
	v_mul_f32_e32 v9, v71, v5
	v_cndmask_b32_e32 v10, v1, v9, vcc
	ds_bpermute_b32 v10, v212, v10
	s_waitcnt lgkmcnt(0)
	v_cndmask_b32_e32 v1, v10, v1, vcc
	v_cndmask_b32_e32 v9, v9, v10, vcc
	v_or_b32_e32 v10, 0x8000, v2
	s_waitcnt vmcnt(31)
	v_lshlrev_b32_e32 v12, 16, v91
	v_and_b32_e32 v11, 0xffff0000, v91
	v_mul_f32_e32 v1, v1, v12
	v_mul_f32_e32 v9, v9, v11
	v_cvt_pk_bf16_f32 v1, v1, v9
	global_store_dword v10, v1, s[44:45]
	v_mul_f32_e32 v1, v54, v4
	v_mul_f32_e32 v9, v55, v5
	v_cndmask_b32_e32 v11, v1, v9, vcc
	ds_bpermute_b32 v11, v212, v11
	s_waitcnt lgkmcnt(0)
	v_cndmask_b32_e32 v1, v11, v1, vcc
	v_cndmask_b32_e32 v9, v9, v11, vcc
	s_waitcnt vmcnt(31)
	v_lshlrev_b32_e32 v12, 16, v92
	v_and_b32_e32 v11, 0xffff0000, v92
	v_mul_f32_e32 v1, v1, v12
	v_mul_f32_e32 v9, v9, v11
	v_cvt_pk_bf16_f32 v1, v1, v9
	global_store_dword v10, v1, s[44:45] offset:64
	v_mul_f32_e32 v1, v38, v4
	v_mul_f32_e32 v9, v39, v5
	v_cndmask_b32_e32 v11, v1, v9, vcc
	ds_bpermute_b32 v11, v212, v11
	s_waitcnt lgkmcnt(0)
	v_cndmask_b32_e32 v1, v11, v1, vcc
	v_cndmask_b32_e32 v9, v9, v11, vcc
	s_waitcnt vmcnt(31)
	v_lshlrev_b32_e32 v12, 16, v93
	v_and_b32_e32 v11, 0xffff0000, v93
	v_mul_f32_e32 v1, v1, v12
	v_mul_f32_e32 v9, v9, v11
	v_cvt_pk_bf16_f32 v1, v1, v9
	global_store_dword v10, v1, s[44:45] offset:128
	v_mul_f32_e32 v1, v22, v4
	v_mul_f32_e32 v4, v23, v5
	v_cndmask_b32_e32 v5, v1, v4, vcc
	ds_bpermute_b32 v5, v212, v5
	s_waitcnt lgkmcnt(0)
	v_cndmask_b32_e32 v1, v5, v1, vcc
	v_cndmask_b32_e32 v4, v4, v5, vcc
	s_waitcnt vmcnt(31)
	v_lshlrev_b32_e32 v9, 16, v94
	v_and_b32_e32 v5, 0xffff0000, v94
	v_mul_f32_e32 v1, v1, v9
	v_mul_f32_e32 v4, v4, v5
	v_cvt_pk_bf16_f32 v1, v1, v4
	global_store_dword v10, v1, s[44:45] offset:192
	v_rcp_f32_e32 v1, v6
	v_rcp_f32_e32 v4, v7
	v_mul_f32_e32 v5, v72, v1
	v_mul_f32_e32 v6, v73, v4
	v_cndmask_b32_e32 v7, v5, v6, vcc
	ds_bpermute_b32 v7, v212, v7
	s_waitcnt lgkmcnt(0)
	v_cndmask_b32_e32 v5, v7, v5, vcc
	v_cndmask_b32_e32 v6, v6, v7, vcc
	v_or_b32_e32 v7, 0xa000, v2
	s_waitcnt vmcnt(31)
	v_lshlrev_b32_e32 v10, 16, v95
	v_and_b32_e32 v9, 0xffff0000, v95
	v_mul_f32_e32 v5, v5, v10
	v_mul_f32_e32 v6, v6, v9
	v_cvt_pk_bf16_f32 v5, v5, v6
	global_store_dword v7, v5, s[44:45]
	v_mul_f32_e32 v5, v56, v1
	v_mul_f32_e32 v6, v57, v4
	v_cndmask_b32_e32 v9, v5, v6, vcc
	ds_bpermute_b32 v9, v212, v9
	s_waitcnt lgkmcnt(0)
	v_cndmask_b32_e32 v5, v9, v5, vcc
	v_cndmask_b32_e32 v6, v6, v9, vcc
	s_waitcnt vmcnt(31)
	v_lshlrev_b32_e32 v10, 16, v96
	v_and_b32_e32 v9, 0xffff0000, v96
	v_mul_f32_e32 v5, v5, v10
	v_mul_f32_e32 v6, v6, v9
	v_cvt_pk_bf16_f32 v5, v5, v6
	global_store_dword v7, v5, s[44:45] offset:64
	v_mul_f32_e32 v5, v40, v1
	v_mul_f32_e32 v6, v41, v4
	v_cndmask_b32_e32 v9, v5, v6, vcc
	ds_bpermute_b32 v9, v212, v9
	v_mul_f32_e32 v1, v24, v1
	v_mul_f32_e32 v4, v25, v4
	s_waitcnt lgkmcnt(0)
	v_cndmask_b32_e32 v5, v9, v5, vcc
	v_cndmask_b32_e32 v6, v6, v9, vcc
	s_waitcnt vmcnt(31)
	v_lshlrev_b32_e32 v10, 16, v97
	v_and_b32_e32 v9, 0xffff0000, v97
	v_mul_f32_e32 v5, v5, v10
	v_mul_f32_e32 v6, v6, v9
	v_cvt_pk_bf16_f32 v5, v5, v6
	global_store_dword v7, v5, s[44:45] offset:128
	v_cndmask_b32_e32 v5, v1, v4, vcc
	ds_bpermute_b32 v5, v212, v5
	s_waitcnt lgkmcnt(0)
	v_cndmask_b32_e32 v1, v5, v1, vcc
	v_cndmask_b32_e32 v4, v4, v5, vcc
	s_waitcnt vmcnt(31)
	v_lshlrev_b32_e32 v6, 16, v98
	v_and_b32_e32 v5, 0xffff0000, v98
	v_mul_f32_e32 v1, v1, v6
	v_mul_f32_e32 v4, v4, v5
	v_cvt_pk_bf16_f32 v1, v1, v4
	global_store_dword v7, v1, s[44:45] offset:192
	ds_read_b128 v[4:7], v8 offset:64
	s_waitcnt lgkmcnt(0)
	v_rcp_f32_e32 v1, v4
	v_rcp_f32_e32 v4, v5
	v_mul_f32_e32 v5, v74, v1
	v_mul_f32_e32 v9, v75, v4
	v_cndmask_b32_e32 v10, v5, v9, vcc
	ds_bpermute_b32 v10, v212, v10
	s_waitcnt lgkmcnt(0)
	v_cndmask_b32_e32 v5, v10, v5, vcc
	v_cndmask_b32_e32 v9, v9, v10, vcc
	v_or_b32_e32 v10, 0x10000, v2
	s_waitcnt vmcnt(31)
	v_lshlrev_b32_e32 v12, 16, v99
	v_and_b32_e32 v11, 0xffff0000, v99
	v_mul_f32_e32 v5, v5, v12
	v_mul_f32_e32 v9, v9, v11
	v_cvt_pk_bf16_f32 v5, v5, v9
	global_store_dword v10, v5, s[44:45]
	v_mul_f32_e32 v5, v58, v1
	v_mul_f32_e32 v9, v59, v4
	v_cndmask_b32_e32 v11, v5, v9, vcc
	ds_bpermute_b32 v11, v212, v11
	s_waitcnt lgkmcnt(0)
	v_cndmask_b32_e32 v5, v11, v5, vcc
	v_cndmask_b32_e32 v9, v9, v11, vcc
	s_waitcnt vmcnt(31)
	v_lshlrev_b32_e32 v12, 16, v100
	v_and_b32_e32 v11, 0xffff0000, v100
	v_mul_f32_e32 v5, v5, v12
	v_mul_f32_e32 v9, v9, v11
	v_cvt_pk_bf16_f32 v5, v5, v9
	global_store_dword v10, v5, s[44:45] offset:64
	v_mul_f32_e32 v5, v42, v1
	v_mul_f32_e32 v9, v43, v4
	v_cndmask_b32_e32 v11, v5, v9, vcc
	ds_bpermute_b32 v11, v212, v11
	v_mul_f32_e32 v1, v26, v1
	v_mul_f32_e32 v4, v27, v4
	s_waitcnt lgkmcnt(0)
	v_cndmask_b32_e32 v5, v11, v5, vcc
	v_cndmask_b32_e32 v9, v9, v11, vcc
	s_waitcnt vmcnt(31)
	v_lshlrev_b32_e32 v12, 16, v101
	v_and_b32_e32 v11, 0xffff0000, v101
	v_mul_f32_e32 v5, v5, v12
	v_mul_f32_e32 v9, v9, v11
	v_cvt_pk_bf16_f32 v5, v5, v9
	global_store_dword v10, v5, s[44:45] offset:128
	v_cndmask_b32_e32 v5, v1, v4, vcc
	ds_bpermute_b32 v5, v212, v5
	s_waitcnt lgkmcnt(0)
	v_cndmask_b32_e32 v1, v5, v1, vcc
	v_cndmask_b32_e32 v4, v4, v5, vcc
	s_waitcnt vmcnt(31)
	v_lshlrev_b32_e32 v9, 16, v102
	v_and_b32_e32 v5, 0xffff0000, v102
	v_mul_f32_e32 v1, v1, v9
	v_mul_f32_e32 v4, v4, v5
	v_cvt_pk_bf16_f32 v1, v1, v4
	global_store_dword v10, v1, s[44:45] offset:192
	v_rcp_f32_e32 v1, v6
	v_rcp_f32_e32 v4, v7
	v_mul_f32_e32 v5, v76, v1
	v_mul_f32_e32 v6, v77, v4
	v_cndmask_b32_e32 v7, v5, v6, vcc
	ds_bpermute_b32 v7, v212, v7
	s_waitcnt lgkmcnt(0)
	v_cndmask_b32_e32 v5, v7, v5, vcc
	v_cndmask_b32_e32 v6, v6, v7, vcc
	v_or_b32_e32 v7, 0x12000, v2
	s_waitcnt vmcnt(31)
	v_lshlrev_b32_e32 v10, 16, v103
	v_and_b32_e32 v9, 0xffff0000, v103
	v_mul_f32_e32 v5, v5, v10
	v_mul_f32_e32 v6, v6, v9
	v_cvt_pk_bf16_f32 v5, v5, v6
	global_store_dword v7, v5, s[44:45]
	v_mul_f32_e32 v5, v60, v1
	v_mul_f32_e32 v6, v61, v4
	v_cndmask_b32_e32 v9, v5, v6, vcc
	ds_bpermute_b32 v9, v212, v9
	s_waitcnt lgkmcnt(0)
	v_cndmask_b32_e32 v5, v9, v5, vcc
	v_cndmask_b32_e32 v6, v6, v9, vcc
	s_waitcnt vmcnt(31)
	v_lshlrev_b32_e32 v10, 16, v104
	v_and_b32_e32 v9, 0xffff0000, v104
	v_mul_f32_e32 v5, v5, v10
	v_mul_f32_e32 v6, v6, v9
	v_cvt_pk_bf16_f32 v5, v5, v6
	global_store_dword v7, v5, s[44:45] offset:64
	v_mul_f32_e32 v5, v44, v1
	v_mul_f32_e32 v6, v45, v4
	v_cndmask_b32_e32 v9, v5, v6, vcc
	ds_bpermute_b32 v9, v212, v9
	v_mul_f32_e32 v1, v28, v1
	v_mul_f32_e32 v4, v29, v4
	s_waitcnt lgkmcnt(0)
	v_cndmask_b32_e32 v5, v9, v5, vcc
	v_cndmask_b32_e32 v6, v6, v9, vcc
	s_waitcnt vmcnt(31)
	v_lshlrev_b32_e32 v10, 16, v105
	v_and_b32_e32 v9, 0xffff0000, v105
	v_mul_f32_e32 v5, v5, v10
	v_mul_f32_e32 v6, v6, v9
	v_cvt_pk_bf16_f32 v5, v5, v6
	global_store_dword v7, v5, s[44:45] offset:128
	v_cndmask_b32_e32 v5, v1, v4, vcc
	ds_bpermute_b32 v5, v212, v5
	s_waitcnt lgkmcnt(0)
	v_cndmask_b32_e32 v1, v5, v1, vcc
	v_cndmask_b32_e32 v4, v4, v5, vcc
	s_waitcnt vmcnt(31)
	v_lshlrev_b32_e32 v6, 16, v106
	v_and_b32_e32 v5, 0xffff0000, v106
	v_mul_f32_e32 v1, v1, v6
	v_mul_f32_e32 v4, v4, v5
	v_cvt_pk_bf16_f32 v1, v1, v4
	global_store_dword v7, v1, s[44:45] offset:192
	ds_read_b128 v[4:7], v8 offset:96
	s_waitcnt lgkmcnt(0)
	v_rcp_f32_e32 v4, v4
	v_rcp_f32_e32 v5, v5
	v_mul_f32_e32 v1, v78, v4
	v_mul_f32_e32 v8, v79, v5
	v_cndmask_b32_e32 v9, v1, v8, vcc
	ds_bpermute_b32 v9, v212, v9
	s_waitcnt lgkmcnt(0)
	v_cndmask_b32_e32 v1, v9, v1, vcc
	v_cndmask_b32_e32 v8, v8, v9, vcc
	v_or_b32_e32 v9, 0x18000, v2
	v_or_b32_e32 v2, 0x1a000, v2
	s_waitcnt vmcnt(31)
	v_lshlrev_b32_e32 v11, 16, v107
	v_and_b32_e32 v10, 0xffff0000, v107
	v_mul_f32_e32 v1, v1, v11
	v_mul_f32_e32 v8, v8, v10
	v_cvt_pk_bf16_f32 v1, v1, v8
	global_store_dword v9, v1, s[44:45]
	v_mul_f32_e32 v1, v62, v4
	v_mul_f32_e32 v8, v63, v5
	v_cndmask_b32_e32 v10, v1, v8, vcc
	ds_bpermute_b32 v10, v212, v10
	s_waitcnt lgkmcnt(0)
	v_cndmask_b32_e32 v1, v10, v1, vcc
	v_cndmask_b32_e32 v8, v8, v10, vcc
	s_waitcnt vmcnt(31)
	v_lshlrev_b32_e32 v11, 16, v108
	v_and_b32_e32 v10, 0xffff0000, v108
	v_mul_f32_e32 v1, v1, v11
	v_mul_f32_e32 v8, v8, v10
	v_cvt_pk_bf16_f32 v1, v1, v8
	global_store_dword v9, v1, s[44:45] offset:64
	v_mul_f32_e32 v1, v46, v4
	v_mul_f32_e32 v8, v47, v5
	v_cndmask_b32_e32 v10, v1, v8, vcc
	ds_bpermute_b32 v10, v212, v10
	s_waitcnt lgkmcnt(0)
	v_cndmask_b32_e32 v1, v10, v1, vcc
	v_cndmask_b32_e32 v8, v8, v10, vcc
	s_waitcnt vmcnt(31)
	v_lshlrev_b32_e32 v11, 16, v109
	v_and_b32_e32 v10, 0xffff0000, v109
	v_mul_f32_e32 v1, v1, v11
	v_mul_f32_e32 v8, v8, v10
	v_cvt_pk_bf16_f32 v1, v1, v8
	global_store_dword v9, v1, s[44:45] offset:128
	v_mul_f32_e32 v1, v30, v4
	v_mul_f32_e32 v4, v31, v5
	v_cndmask_b32_e32 v5, v1, v4, vcc
	ds_bpermute_b32 v5, v212, v5
	s_waitcnt lgkmcnt(0)
	v_cndmask_b32_e32 v1, v5, v1, vcc
	v_cndmask_b32_e32 v4, v4, v5, vcc
	s_waitcnt vmcnt(31)
	v_lshlrev_b32_e32 v8, 16, v110
	v_and_b32_e32 v5, 0xffff0000, v110
	v_mul_f32_e32 v1, v1, v8
	v_mul_f32_e32 v4, v4, v5
	v_cvt_pk_bf16_f32 v1, v1, v4
	global_store_dword v9, v1, s[44:45] offset:192
	v_rcp_f32_e32 v1, v6
	v_rcp_f32_e32 v4, v7
	v_mul_f32_e32 v5, v80, v1
	v_mul_f32_e32 v6, v81, v4
	v_cndmask_b32_e32 v7, v5, v6, vcc
	ds_bpermute_b32 v7, v212, v7
	s_waitcnt lgkmcnt(0)
	v_cndmask_b32_e32 v5, v7, v5, vcc
	v_cndmask_b32_e32 v6, v6, v7, vcc
	s_waitcnt vmcnt(31)
	v_lshlrev_b32_e32 v8, 16, v111
	v_and_b32_e32 v7, 0xffff0000, v111
	v_mul_f32_e32 v5, v5, v8
	v_mul_f32_e32 v6, v6, v7
	v_cvt_pk_bf16_f32 v5, v5, v6
	global_store_dword v2, v5, s[44:45]
	v_mul_f32_e32 v5, v64, v1
	v_mul_f32_e32 v6, v65, v4
	v_cndmask_b32_e32 v7, v5, v6, vcc
	ds_bpermute_b32 v7, v212, v7
	s_waitcnt lgkmcnt(0)
	v_cndmask_b32_e32 v5, v7, v5, vcc
	v_cndmask_b32_e32 v6, v6, v7, vcc
	s_waitcnt vmcnt(31)
	v_lshlrev_b32_e32 v8, 16, v112
	v_and_b32_e32 v7, 0xffff0000, v112
	v_mul_f32_e32 v5, v5, v8
	v_mul_f32_e32 v6, v6, v7
	v_cvt_pk_bf16_f32 v5, v5, v6
	global_store_dword v2, v5, s[44:45] offset:64
	v_mul_f32_e32 v5, v48, v1
	v_mul_f32_e32 v6, v49, v4
	v_cndmask_b32_e32 v7, v5, v6, vcc
	ds_bpermute_b32 v7, v212, v7
	v_mul_f32_e32 v1, v32, v1
	v_mul_f32_e32 v4, v33, v4
	s_waitcnt lgkmcnt(0)
	v_cndmask_b32_e32 v5, v7, v5, vcc
	v_cndmask_b32_e32 v6, v6, v7, vcc
	s_waitcnt vmcnt(31)
	v_lshlrev_b32_e32 v8, 16, v113
	v_and_b32_e32 v7, 0xffff0000, v113
	v_mul_f32_e32 v5, v5, v8
	v_mul_f32_e32 v6, v6, v7
	v_cvt_pk_bf16_f32 v5, v5, v6
	global_store_dword v2, v5, s[44:45] offset:128
	v_cndmask_b32_e32 v5, v1, v4, vcc
	ds_bpermute_b32 v5, v212, v5
	s_waitcnt lgkmcnt(0)
	v_cndmask_b32_e32 v1, v5, v1, vcc
	v_cndmask_b32_e32 v4, v4, v5, vcc
	s_waitcnt vmcnt(31)
	v_lshlrev_b32_e32 v6, 16, v114
	v_and_b32_e32 v5, 0xffff0000, v114
	v_mul_f32_e32 v1, v1, v6
	v_mul_f32_e32 v4, v4, v5
	v_cvt_pk_bf16_f32 v1, v1, v4
	global_store_dword v2, v1, s[44:45] offset:192
	s_mov_b64 s[44:45], 0
